# P1 and P9 hand-written: per-wave gain/scale/shift vectors loaded once, three rows of x in flight, P9 row loads issued up front
# baseline (speedup 1.0000x reference)
.LBB0_1723:
	s_cmp_lt_i32 s78, 10
	s_cselect_b64 s[2:3], -1, 0
	s_and_b64 s[0:1], s[2:3], s[0:1]
	s_andn2_b64 vcc, exec, s[0:1]
	s_cbranch_vccnz .LBB0_1731
	s_cmpk_lg_i32 s92, 0x100
	s_cbranch_scc1 .Lp9_generic
	v_readlane_b32 s1, v253, 45
	v_readlane_b32 s2, v253, 20
	v_readlane_b32 s3, v253, 21
	v_readlane_b32 s12, v253, 18
	v_readlane_b32 s13, v253, 19
	s_lshl_b32 s0, s96, 3
	s_add_i32 s0, s0, s1
	s_lshl_b32 s14, s0, 13
	s_add_u32 s2, s2, s14
	s_addc_u32 s3, s3, 0
	s_add_u32 s2, s2, 0x4000000
	s_addc_u32 s3, s3, 0
	s_add_u32 s4, s76, s14
	s_addc_u32 s5, s77, 0
	s_add_u32 s4, s4, 0x12000000
	s_addc_u32 s5, s5, 0
	s_add_u32 s6, s4, 0x1000000
	s_addc_u32 s7, s5, 0
	s_add_u32 s8, s6, 0x1000000
	s_addc_u32 s9, s7, 0
	s_add_u32 s10, s8, 0x1000000
	s_addc_u32 s11, s9, 0
	v_lshlrev_b32_e32 v232, 4, v242
	v_add_u32_e32 v233, 0x1000, v232
	v_mov_b32_e32 v235, 0x358637bd
	v_xor_b32_e32 v224, 1, v242
	v_lshlrev_b32_e32 v224, 2, v224
	v_xor_b32_e32 v225, 2, v242
	v_lshlrev_b32_e32 v225, 2, v225
	v_xor_b32_e32 v226, 4, v242
	v_lshlrev_b32_e32 v226, 2, v226
	v_xor_b32_e32 v227, 8, v242
	v_lshlrev_b32_e32 v227, 2, v227
	v_xor_b32_e32 v228, 16, v242
	v_lshlrev_b32_e32 v228, 2, v228
	v_xor_b32_e32 v229, 32, v242
	v_lshlrev_b32_e32 v229, 2, v229
	global_load_dwordx4 v[0:3], v232, s[2:3] offset:0
	global_load_dwordx4 v[4:7], v232, s[2:3] offset:1024
	global_load_dwordx4 v[8:11], v232, s[2:3] offset:2048
	global_load_dwordx4 v[12:15], v232, s[2:3] offset:3072
	global_load_dwordx4 v[16:19], v233, s[2:3] offset:0
	global_load_dwordx4 v[20:23], v233, s[2:3] offset:1024
	global_load_dwordx4 v[24:27], v233, s[2:3] offset:2048
	global_load_dwordx4 v[28:31], v233, s[2:3] offset:3072
	global_load_dwordx4 v[32:35], v232, s[4:5] offset:0 nt
	global_load_dwordx4 v[36:39], v232, s[4:5] offset:1024 nt
	global_load_dwordx4 v[40:43], v232, s[4:5] offset:2048 nt
	global_load_dwordx4 v[44:47], v232, s[4:5] offset:3072 nt
	global_load_dwordx4 v[48:51], v233, s[4:5] offset:0 nt
	global_load_dwordx4 v[52:55], v233, s[4:5] offset:1024 nt
	global_load_dwordx4 v[56:59], v233, s[4:5] offset:2048 nt
	global_load_dwordx4 v[60:63], v233, s[4:5] offset:3072 nt
	global_load_dwordx4 v[64:67], v232, s[6:7] offset:0 nt
	global_load_dwordx4 v[68:71], v232, s[6:7] offset:1024 nt
	global_load_dwordx4 v[72:75], v232, s[6:7] offset:2048 nt
	global_load_dwordx4 v[76:79], v232, s[6:7] offset:3072 nt
	global_load_dwordx4 v[80:83], v233, s[6:7] offset:0 nt
	global_load_dwordx4 v[84:87], v233, s[6:7] offset:1024 nt
	global_load_dwordx4 v[88:91], v233, s[6:7] offset:2048 nt
	global_load_dwordx4 v[92:95], v233, s[6:7] offset:3072 nt
	global_load_dwordx4 v[96:99], v232, s[8:9] offset:0 nt
	global_load_dwordx4 v[100:103], v232, s[8:9] offset:1024 nt
	global_load_dwordx4 v[104:107], v232, s[8:9] offset:2048 nt
	global_load_dwordx4 v[108:111], v232, s[8:9] offset:3072 nt
	global_load_dwordx4 v[112:115], v233, s[8:9] offset:0 nt
	global_load_dwordx4 v[116:119], v233, s[8:9] offset:1024 nt
	global_load_dwordx4 v[120:123], v233, s[8:9] offset:2048 nt
	global_load_dwordx4 v[124:127], v233, s[8:9] offset:3072 nt
	global_load_dwordx4 v[128:131], v232, s[10:11] offset:0 nt
	global_load_dwordx4 v[132:135], v232, s[10:11] offset:1024 nt
	global_load_dwordx4 v[136:139], v232, s[10:11] offset:2048 nt
	global_load_dwordx4 v[140:143], v232, s[10:11] offset:3072 nt
	global_load_dwordx4 v[144:147], v233, s[10:11] offset:0 nt
	global_load_dwordx4 v[148:151], v233, s[10:11] offset:1024 nt
	global_load_dwordx4 v[152:155], v233, s[10:11] offset:2048 nt
	global_load_dwordx4 v[156:159], v233, s[10:11] offset:3072 nt
	global_load_dwordx4 v[160:163], v232, s[12:13] offset:0
	global_load_dwordx4 v[164:167], v232, s[12:13] offset:1024
	global_load_dwordx4 v[168:171], v232, s[12:13] offset:2048
	global_load_dwordx4 v[172:175], v232, s[12:13] offset:3072
	global_load_dwordx4 v[176:179], v233, s[12:13] offset:0
	global_load_dwordx4 v[180:183], v233, s[12:13] offset:1024
	global_load_dwordx4 v[184:187], v233, s[12:13] offset:2048
	global_load_dwordx4 v[188:191], v233, s[12:13] offset:3072
	s_waitcnt vmcnt(0)
	v_pk_add_f32 v[32:33], v[32:33], v[64:65]
	v_pk_add_f32 v[96:97], v[96:97], v[128:129]
	v_pk_add_f32 v[32:33], v[32:33], v[96:97]
	v_pk_add_f32 v[0:1], v[0:1], v[32:33]
	v_pk_add_f32 v[34:35], v[34:35], v[66:67]
	v_pk_add_f32 v[98:99], v[98:99], v[130:131]
	v_pk_add_f32 v[34:35], v[34:35], v[98:99]
	v_pk_add_f32 v[2:3], v[2:3], v[34:35]
	v_pk_add_f32 v[36:37], v[36:37], v[68:69]
	v_pk_add_f32 v[100:101], v[100:101], v[132:133]
	v_pk_add_f32 v[36:37], v[36:37], v[100:101]
	v_pk_add_f32 v[4:5], v[4:5], v[36:37]
	v_pk_add_f32 v[38:39], v[38:39], v[70:71]
	v_pk_add_f32 v[102:103], v[102:103], v[134:135]
	v_pk_add_f32 v[38:39], v[38:39], v[102:103]
	v_pk_add_f32 v[6:7], v[6:7], v[38:39]
	v_pk_add_f32 v[40:41], v[40:41], v[72:73]
	v_pk_add_f32 v[104:105], v[104:105], v[136:137]
	v_pk_add_f32 v[40:41], v[40:41], v[104:105]
	v_pk_add_f32 v[8:9], v[8:9], v[40:41]
	v_pk_add_f32 v[42:43], v[42:43], v[74:75]
	v_pk_add_f32 v[106:107], v[106:107], v[138:139]
	v_pk_add_f32 v[42:43], v[42:43], v[106:107]
	v_pk_add_f32 v[10:11], v[10:11], v[42:43]
	v_pk_add_f32 v[44:45], v[44:45], v[76:77]
	v_pk_add_f32 v[108:109], v[108:109], v[140:141]
	v_pk_add_f32 v[44:45], v[44:45], v[108:109]
	v_pk_add_f32 v[12:13], v[12:13], v[44:45]
	v_pk_add_f32 v[46:47], v[46:47], v[78:79]
	v_pk_add_f32 v[110:111], v[110:111], v[142:143]
	v_pk_add_f32 v[46:47], v[46:47], v[110:111]
	v_pk_add_f32 v[14:15], v[14:15], v[46:47]
	v_pk_add_f32 v[48:49], v[48:49], v[80:81]
	v_pk_add_f32 v[112:113], v[112:113], v[144:145]
	v_pk_add_f32 v[48:49], v[48:49], v[112:113]
	v_pk_add_f32 v[16:17], v[16:17], v[48:49]
	v_pk_add_f32 v[50:51], v[50:51], v[82:83]
	v_pk_add_f32 v[114:115], v[114:115], v[146:147]
	v_pk_add_f32 v[50:51], v[50:51], v[114:115]
	v_pk_add_f32 v[18:19], v[18:19], v[50:51]
	v_pk_add_f32 v[52:53], v[52:53], v[84:85]
	v_pk_add_f32 v[116:117], v[116:117], v[148:149]
	v_pk_add_f32 v[52:53], v[52:53], v[116:117]
	v_pk_add_f32 v[20:21], v[20:21], v[52:53]
	v_pk_add_f32 v[54:55], v[54:55], v[86:87]
	v_pk_add_f32 v[118:119], v[118:119], v[150:151]
	v_pk_add_f32 v[54:55], v[54:55], v[118:119]
	v_pk_add_f32 v[22:23], v[22:23], v[54:55]
	v_pk_add_f32 v[56:57], v[56:57], v[88:89]
	v_pk_add_f32 v[120:121], v[120:121], v[152:153]
	v_pk_add_f32 v[56:57], v[56:57], v[120:121]
	v_pk_add_f32 v[24:25], v[24:25], v[56:57]
	v_pk_add_f32 v[58:59], v[58:59], v[90:91]
	v_pk_add_f32 v[122:123], v[122:123], v[154:155]
	v_pk_add_f32 v[58:59], v[58:59], v[122:123]
	v_pk_add_f32 v[26:27], v[26:27], v[58:59]
	v_pk_add_f32 v[60:61], v[60:61], v[92:93]
	v_pk_add_f32 v[124:125], v[124:125], v[156:157]
	v_pk_add_f32 v[60:61], v[60:61], v[124:125]
	v_pk_add_f32 v[28:29], v[28:29], v[60:61]
	v_pk_add_f32 v[62:63], v[62:63], v[94:95]
	v_pk_add_f32 v[126:127], v[126:127], v[158:159]
	v_pk_add_f32 v[62:63], v[62:63], v[126:127]
	v_pk_add_f32 v[30:31], v[30:31], v[62:63]
	v_pk_mul_f32 v[236:237], v[0:1], v[0:1]
	v_pk_fma_f32 v[236:237], v[2:3], v[2:3], v[236:237]
	v_pk_fma_f32 v[236:237], v[4:5], v[4:5], v[236:237]
	v_pk_fma_f32 v[236:237], v[6:7], v[6:7], v[236:237]
	v_pk_fma_f32 v[236:237], v[8:9], v[8:9], v[236:237]
	v_pk_fma_f32 v[236:237], v[10:11], v[10:11], v[236:237]
	v_pk_fma_f32 v[236:237], v[12:13], v[12:13], v[236:237]
	v_pk_fma_f32 v[236:237], v[14:15], v[14:15], v[236:237]
	v_pk_fma_f32 v[236:237], v[16:17], v[16:17], v[236:237]
	v_pk_fma_f32 v[236:237], v[18:19], v[18:19], v[236:237]
	v_pk_fma_f32 v[236:237], v[20:21], v[20:21], v[236:237]
	v_pk_fma_f32 v[236:237], v[22:23], v[22:23], v[236:237]
	v_pk_fma_f32 v[236:237], v[24:25], v[24:25], v[236:237]
	v_pk_fma_f32 v[236:237], v[26:27], v[26:27], v[236:237]
	v_pk_fma_f32 v[236:237], v[28:29], v[28:29], v[236:237]
	v_pk_fma_f32 v[236:237], v[30:31], v[30:31], v[236:237]
	v_add_f32_e32 v236, v236, v237
	ds_bpermute_b32 v237, v224, v236
	s_waitcnt lgkmcnt(0)
	v_add_f32_e32 v236, v236, v237
	ds_bpermute_b32 v237, v225, v236
	s_waitcnt lgkmcnt(0)
	v_add_f32_e32 v236, v236, v237
	ds_bpermute_b32 v237, v226, v236
	s_waitcnt lgkmcnt(0)
	v_add_f32_e32 v236, v236, v237
	ds_bpermute_b32 v237, v227, v236
	s_waitcnt lgkmcnt(0)
	v_add_f32_e32 v236, v236, v237
	ds_bpermute_b32 v237, v228, v236
	s_waitcnt lgkmcnt(0)
	v_add_f32_e32 v236, v236, v237
	ds_bpermute_b32 v237, v229, v236
	s_waitcnt lgkmcnt(0)
	v_add_f32_e32 v236, v236, v237
	v_fmamk_f32 v236, v236, 0x3a000000, v235
	v_rsq_f32_e32 v236, v236
	s_nop 0
	v_pk_mul_f32 v[0:1], v[236:237], v[0:1] op_sel_hi:[0,1]
	v_pk_mul_f32 v[2:3], v[236:237], v[2:3] op_sel_hi:[0,1]
	v_pk_mul_f32 v[0:1], v[0:1], v[160:161]
	v_pk_mul_f32 v[2:3], v[2:3], v[162:163]
	global_store_dwordx4 v232, v[0:3], s[2:3] offset:0 nt
	v_pk_mul_f32 v[4:5], v[236:237], v[4:5] op_sel_hi:[0,1]
	v_pk_mul_f32 v[6:7], v[236:237], v[6:7] op_sel_hi:[0,1]
	v_pk_mul_f32 v[4:5], v[4:5], v[164:165]
	v_pk_mul_f32 v[6:7], v[6:7], v[166:167]
	global_store_dwordx4 v232, v[4:7], s[2:3] offset:1024 nt
	v_pk_mul_f32 v[8:9], v[236:237], v[8:9] op_sel_hi:[0,1]
	v_pk_mul_f32 v[10:11], v[236:237], v[10:11] op_sel_hi:[0,1]
	v_pk_mul_f32 v[8:9], v[8:9], v[168:169]
	v_pk_mul_f32 v[10:11], v[10:11], v[170:171]
	global_store_dwordx4 v232, v[8:11], s[2:3] offset:2048 nt
	v_pk_mul_f32 v[12:13], v[236:237], v[12:13] op_sel_hi:[0,1]
	v_pk_mul_f32 v[14:15], v[236:237], v[14:15] op_sel_hi:[0,1]
	v_pk_mul_f32 v[12:13], v[12:13], v[172:173]
	v_pk_mul_f32 v[14:15], v[14:15], v[174:175]
	global_store_dwordx4 v232, v[12:15], s[2:3] offset:3072 nt
	v_pk_mul_f32 v[16:17], v[236:237], v[16:17] op_sel_hi:[0,1]
	v_pk_mul_f32 v[18:19], v[236:237], v[18:19] op_sel_hi:[0,1]
	v_pk_mul_f32 v[16:17], v[16:17], v[176:177]
	v_pk_mul_f32 v[18:19], v[18:19], v[178:179]
	global_store_dwordx4 v233, v[16:19], s[2:3] offset:0 nt
	v_pk_mul_f32 v[20:21], v[236:237], v[20:21] op_sel_hi:[0,1]
	v_pk_mul_f32 v[22:23], v[236:237], v[22:23] op_sel_hi:[0,1]
	v_pk_mul_f32 v[20:21], v[20:21], v[180:181]
	v_pk_mul_f32 v[22:23], v[22:23], v[182:183]
	global_store_dwordx4 v233, v[20:23], s[2:3] offset:1024 nt
	v_pk_mul_f32 v[24:25], v[236:237], v[24:25] op_sel_hi:[0,1]
	v_pk_mul_f32 v[26:27], v[236:237], v[26:27] op_sel_hi:[0,1]
	v_pk_mul_f32 v[24:25], v[24:25], v[184:185]
	v_pk_mul_f32 v[26:27], v[26:27], v[186:187]
	global_store_dwordx4 v233, v[24:27], s[2:3] offset:2048 nt
	v_pk_mul_f32 v[28:29], v[236:237], v[28:29] op_sel_hi:[0,1]
	v_pk_mul_f32 v[30:31], v[236:237], v[30:31] op_sel_hi:[0,1]
	v_pk_mul_f32 v[28:29], v[28:29], v[188:189]
	v_pk_mul_f32 v[30:31], v[30:31], v[190:191]
	global_store_dwordx4 v233, v[28:31], s[2:3] offset:3072 nt
	s_branch .LBB0_1731
.Lp9_generic:
	s_lshl_b32 s0, s96, 3
	v_readlane_b32 s1, v253, 45
	s_add_i32 s2, s1, s0
	s_cmpk_eq_i32 s92, 0x100
	s_cselect_b64 s[12:13], -1, 0
	s_and_b64 s[0:1], s[12:13], exec
	s_cselect_b32 s0, 0x2000, 0
	s_add_i32 s0, s2, s0
	s_cmpk_gt_i32 s0, 0x27ff
	s_mov_b32 s3, 0
	s_cbranch_scc1 .LBB0_1731
	v_lshlrev_b32_e32 v56, 4, v242
	v_mov_b32_e32 v57, 0
	v_lshl_add_u64 v[0:1], s[76:77], 0, v[56:57]
	s_mov_b64 s[6:7], 0x12000000
	s_ashr_i32 s1, s0, 31
	s_lshl_b32 s4, s92, 3
	v_lshl_add_u64 v[58:59], v[0:1], 0, s[6:7]
	s_lshl_b64 s[6:7], s[0:1], 2
	s_add_u32 s2, s76, s6
	v_readlane_b32 s16, v253, 6
	s_addc_u32 s5, s77, s7
	v_readlane_b32 s20, v253, 10
	v_readlane_b32 s21, v253, 11
	v_readlane_b32 s22, v253, 12
	v_readlane_b32 s23, v253, 13
	v_readlane_b32 s28, v253, 18
	v_readlane_b32 s29, v253, 19
	s_add_u32 s6, s2, 0x4f000
	v_readlane_b32 s30, v253, 20
	v_readlane_b32 s31, v253, 21
	s_mov_b64 s[20:21], s[28:29]
	v_or_b32_e32 v0, 0x1000, v56
	v_mov_b32_e32 v1, v57
	s_addc_u32 s7, s5, 0
	s_ashr_i32 s5, s4, 31
	s_mov_b64 s[22:23], s[30:31]
	v_lshl_add_u64 v[62:63], s[20:21], 0, v[0:1]
	v_or_b32_e32 v0, 0x1400, v56
	s_lshl_b64 s[8:9], s[4:5], 2
	s_lshl_b64 s[10:11], s[0:1], 13
	v_lshl_add_u64 v[64:65], s[20:21], 0, v[0:1]
	v_or_b32_e32 v0, 0x1800, v56
	s_add_u32 s10, s22, s10
	v_lshl_add_u64 v[66:67], s[20:21], 0, v[0:1]
	v_or_b32_e32 v0, 0x1c00, v56
	s_addc_u32 s11, s23, s11
	v_lshl_add_u64 v[68:69], s[20:21], 0, v[0:1]
	v_lshl_add_u64 v[0:1], s[10:11], 0, v[56:57]
	s_mov_b64 s[10:11], 0x1000
	v_lshl_add_u64 v[70:71], v[0:1], 0, s[10:11]
	v_mbcnt_lo_u32_b32 v0, -1, 0
	v_mbcnt_hi_u32_b32 v72, -1, v0
	v_readlane_b32 s17, v253, 7
	v_readlane_b32 s18, v253, 8
	v_and_b32_e32 v0, 64, v72
	v_lshl_add_u64 v[60:61], s[20:21], 0, v[56:57]
	s_movk_i32 s16, 0x1000
	s_lshl_b64 s[10:11], s[4:5], 13
	s_mov_b32 s1, 0x1001000
	s_mov_b32 s5, 0x2001000
	s_mov_b32 s17, 0x3001000
	v_mov_b32_e32 v56, 0x358637bd
	s_mov_b32 s18, 0x800000
	s_xor_b64 s[12:13], s[12:13], -1
	v_add_u32_e32 v73, 64, v0
	v_xor_b32_e32 v74, 1, v72
	v_xor_b32_e32 v75, 2, v72
	v_xor_b32_e32 v76, 4, v72
	v_readlane_b32 s19, v253, 9
	v_readlane_b32 s24, v253, 14
	v_readlane_b32 s25, v253, 15
	v_readlane_b32 s26, v253, 16
	v_readlane_b32 s27, v253, 17
	s_branch .LBB0_1727
